# grid barrier: the XCD leader publishes the generation to its XCD before issuing its own cache invalidate (was after), on top of v24
# speedup vs baseline: 1.0006x; 1.0006x over previous
.LBB0_25:
	s_or_b64 exec, exec, s[8:9]
	buffer_inv sc1
	s_waitcnt vmcnt(0)

.LBB0_161:
	s_or_b64 exec, exec, s[4:5]
	s_mov_b64 s[4:5], exec
	v_mbcnt_lo_u32_b32 v0, s4, 0
	v_mbcnt_hi_u32_b32 v0, s5, v0
	v_cmp_eq_u32_e32 vcc, 0, v0
	s_waitcnt vmcnt(0)
	s_and_saveexec_b64 s[10:11], vcc
	s_cbranch_execz .LBB0_163
	s_bcnt1_i32_b64 s3, s[4:5]
	v_mov_b32_e32 v0, s3
	global_atomic_add v238, v0, s[6:7] offset:1024
.LBB0_163:
	s_or_b64 exec, exec, s[10:11]
	buffer_inv sc1
	s_waitcnt vmcnt(0)

.LBB0_343:
	s_or_b64 exec, exec, s[6:7]
	s_mov_b64 s[6:7], exec
	v_mbcnt_lo_u32_b32 v0, s6, 0
	v_mbcnt_hi_u32_b32 v0, s7, v0
	v_cmp_eq_u32_e32 vcc, 0, v0
	s_waitcnt vmcnt(0)
	s_and_saveexec_b64 s[10:11], vcc
	s_cbranch_execz .LBB0_345
	s_bcnt1_i32_b64 s3, s[6:7]
	v_mov_b32_e32 v0, s3
	global_atomic_add v238, v0, s[8:9] offset:1024

.LBB0_518:
	s_or_b64 exec, exec, s[4:5]
	s_mov_b64 s[4:5], exec
	v_mbcnt_lo_u32_b32 v0, s4, 0
	v_mbcnt_hi_u32_b32 v0, s5, v0
	v_cmp_eq_u32_e32 vcc, 0, v0
	s_waitcnt vmcnt(0)
	s_and_saveexec_b64 s[8:9], vcc
	s_cbranch_execz .LBB0_520
	s_bcnt1_i32_b64 s3, s[4:5]
	v_mov_b32_e32 v0, s3
	global_atomic_add v238, v0, s[6:7] offset:1024

.LBB0_703:
	s_or_b64 exec, exec, s[4:5]
	s_mov_b64 s[4:5], exec
	v_mbcnt_lo_u32_b32 v0, s4, 0
	v_mbcnt_hi_u32_b32 v0, s5, v0
	v_cmp_eq_u32_e32 vcc, 0, v0
	s_waitcnt vmcnt(0)
	s_and_saveexec_b64 s[8:9], vcc
	s_cbranch_execz .LBB0_165
	s_bcnt1_i32_b64 s3, s[4:5]
	v_mov_b32_e32 v0, s3
	global_atomic_add v238, v0, s[6:7] offset:1024
	s_branch .LBB0_165
